# grid barrier: buffer_inv sc1 issued at barrier entry (overlaps arrival atomics) instead of after release
# speedup vs baseline: 1.0046x; 1.0046x over previous
; __device__ __forceinline__ unsigned xb_add(unsigned* p, unsigned v) { return __hip_atomic_fetch_add(p, v, __ATOMIC_RELAXED, __HIP_MEMORY_SCOPE_AGENT); }
; __device__ __forceinline__ void xcd_barrier(const XcdBarrier& b) {
;     asm volatile("s_waitcnt vmcnt(0)" ::: "memory");
;     __syncthreads();
;     if (threadIdx.x == 0) {
;         unsigned* bar = b.bar;
;         __builtin_amdgcn_s_waitcnt(0);
;         unsigned nloc = b.st[0], nx = b.st[1];
;         if (nloc == 0u) { xcd_barrier_complete(bar, b.x, nloc, nx); b.st[0] = nloc; b.st[1] = nx; }
;         const unsigned old = xb_add(&bar[XB_XSUB(b.x)], 1u);
.LBB0_24:
	s_waitcnt vmcnt(0)
	s_waitcnt lgkmcnt(0)
	s_barrier
	s_mov_b64 s[0:1], exec
	v_readlane_b32 s6, v254, 9
	v_readlane_b32 s7, v254, 10
	s_and_b64 s[6:7], s[0:1], s[6:7]
	s_mov_b64 exec, s[6:7]
	s_cbranch_execz .LBB0_75
	s_add_i32 s3, 0, 0x23fc0
	v_mov_b32_e32 v1, s3
	s_waitcnt vmcnt(0) expcnt(0) lgkmcnt(0)
	buffer_inv sc1
	ds_read_b32 v3, v1
	s_add_i32 s3, 0, 0x23fc4
	v_mov_b32_e32 v1, s3
	ds_read_b32 v1, v1
	s_waitcnt lgkmcnt(1)
	v_cmp_ne_u32_e32 vcc, 0, v3
	s_cbranch_vccnz .LBB0_41
	s_add_u32 s6, s30, 0x1000
	s_addc_u32 s7, s31, 0
	s_add_u32 s8, s30, 0x1100
	s_addc_u32 s9, s31, 0
	s_add_u32 s10, s30, 0x1200
	v_readlane_b32 s3, v254, 8
	s_addc_u32 s11, s31, 0
	s_mul_i32 s3, s69, s3
	s_add_u32 s16, s30, 0x1300
	s_mul_i32 s3, s3, s68
	s_addc_u32 s17, s31, 0
	s_mov_b32 s13, 1
	v_mov_b32_e32 v17, 0
	s_branch .LBB0_28

; __device__ __forceinline__ unsigned xb_ld(unsigned* p)              { return __hip_atomic_load(p, __ATOMIC_RELAXED, __HIP_MEMORY_SCOPE_AGENT); }
; #define XB_SPIN(cond, bar) do { unsigned _sp = 0; while (cond) { __builtin_amdgcn_s_sleep(4); \
;     if ((++_sp & 255u) == 0u) { if (xb_ld(&(bar)[XB_TMO])) break; if (_sp > XB_SPIN_CAP) { atomicAdd(&(bar)[XB_TMO], 1u); break; } } } } while (0)
; __device__ __forceinline__ void xcd_barrier(const XcdBarrier& b) {
;     ...
;             else XB_SPIN(xb_ld(&bar[XB_TOPGEN]) == tg, bar);
;             __builtin_amdgcn_fence(__ATOMIC_ACQUIRE, "agent");
;             asm volatile("s_waitcnt vmcnt(0)" ::: "memory");
;         } else {
;             XB_SPIN(xb_ld(&bar[XB_TOPGEN]) == gen, bar);
;             __builtin_amdgcn_fence(__ATOMIC_ACQUIRE, "agent");
;             asm volatile("s_waitcnt vmcnt(0)" ::: "memory");
.LBB0_56:
	s_or_b64 exec, exec, s[8:9]
	s_waitcnt vmcnt(0)
	s_waitcnt vmcnt(0)

; __device__ __forceinline__ unsigned xb_ld(unsigned* p)              { return __hip_atomic_load(p, __ATOMIC_RELAXED, __HIP_MEMORY_SCOPE_AGENT); }
; #define XB_SPIN(cond, bar) do { unsigned _sp = 0; while (cond) { __builtin_amdgcn_s_sleep(4); \
;     if ((++_sp & 255u) == 0u) { if (xb_ld(&(bar)[XB_TMO])) break; if (_sp > XB_SPIN_CAP) { atomicAdd(&(bar)[XB_TMO], 1u); break; } } } } while (0)
; __device__ __forceinline__ void xcd_barrier(const XcdBarrier& b) {
;     ...
;             else XB_SPIN(xb_ld(&bar[XB_TOPGEN]) == tg, bar);
;             __builtin_amdgcn_fence(__ATOMIC_ACQUIRE, "agent");
;             asm volatile("s_waitcnt vmcnt(0)" ::: "memory");
;         } else {
;             XB_SPIN(xb_ld(&bar[XB_TOPGEN]) == gen, bar);
;             __builtin_amdgcn_fence(__ATOMIC_ACQUIRE, "agent");
;             asm volatile("s_waitcnt vmcnt(0)" ::: "memory");
.LBB0_74:
	s_or_b64 exec, exec, s[6:7]
	s_waitcnt vmcnt(0)
	s_waitcnt vmcnt(0)

; __device__ __forceinline__ unsigned xb_add(unsigned* p, unsigned v) { return __hip_atomic_fetch_add(p, v, __ATOMIC_RELAXED, __HIP_MEMORY_SCOPE_AGENT); }
; __device__ __forceinline__ void xcd_barrier(const XcdBarrier& b) {
;     asm volatile("s_waitcnt vmcnt(0)" ::: "memory");
;     __syncthreads();
;     if (threadIdx.x == 0) {
;         unsigned* bar = b.bar;
;         __builtin_amdgcn_s_waitcnt(0);
;         unsigned nloc = b.st[0], nx = b.st[1];
;         if (nloc == 0u) { xcd_barrier_complete(bar, b.x, nloc, nx); b.st[0] = nloc; b.st[1] = nx; }
;         const unsigned old = xb_add(&bar[XB_XSUB(b.x)], 1u);
.LBB0_211:
	s_waitcnt vmcnt(0)
	s_waitcnt vmcnt(0)
	s_barrier
	s_mov_b64 s[0:1], exec
	v_readlane_b32 s4, v254, 9
	v_readlane_b32 s5, v254, 10
	s_and_b64 s[4:5], s[0:1], s[4:5]
	s_mov_b64 exec, s[4:5]
	s_cbranch_execz .LBB0_261
	s_add_i32 s3, 0, 0x23fc0
	v_mov_b32_e32 v0, s3
	s_waitcnt vmcnt(0) expcnt(0) lgkmcnt(0)
	buffer_inv sc1
	ds_read_b32 v2, v0
	s_add_i32 s3, 0, 0x23fc4
	v_mov_b32_e32 v0, s3
	ds_read_b32 v0, v0
	s_waitcnt lgkmcnt(1)
	v_cmp_ne_u32_e32 vcc, 0, v2
	s_cbranch_vccnz .LBB0_227
	s_add_u32 s4, s30, 0x1000
	s_addc_u32 s5, s31, 0
	s_add_u32 s6, s30, 0x1100
	s_addc_u32 s7, s31, 0
	s_add_u32 s8, s30, 0x1200
	v_readlane_b32 s3, v254, 8
	s_addc_u32 s9, s31, 0
	s_mul_i32 s3, s87, s3
	s_add_u32 s20, s30, 0x1300
	s_mul_i32 s3, s3, s86
	s_addc_u32 s21, s31, 0
	s_mov_b32 s13, 1
	v_mov_b32_e32 v16, 0
	s_branch .LBB0_215

; __device__ __forceinline__ unsigned xb_ld(unsigned* p)              { return __hip_atomic_load(p, __ATOMIC_RELAXED, __HIP_MEMORY_SCOPE_AGENT); }
; #define XB_SPIN(cond, bar) do { unsigned _sp = 0; while (cond) { __builtin_amdgcn_s_sleep(4); \
;     if ((++_sp & 255u) == 0u) { if (xb_ld(&(bar)[XB_TMO])) break; if (_sp > XB_SPIN_CAP) { atomicAdd(&(bar)[XB_TMO], 1u); break; } } } } while (0)
; __device__ __forceinline__ void xcd_barrier(const XcdBarrier& b) {
;     ...
;             else XB_SPIN(xb_ld(&bar[XB_TOPGEN]) == tg, bar);
;             __builtin_amdgcn_fence(__ATOMIC_ACQUIRE, "agent");
;             asm volatile("s_waitcnt vmcnt(0)" ::: "memory");
;         } else {
;             XB_SPIN(xb_ld(&bar[XB_TOPGEN]) == gen, bar);
;             __builtin_amdgcn_fence(__ATOMIC_ACQUIRE, "agent");
;             asm volatile("s_waitcnt vmcnt(0)" ::: "memory");
.LBB0_260:
	s_or_b64 exec, exec, s[4:5]
	s_waitcnt vmcnt(0)
	s_waitcnt vmcnt(0)

; __device__ __forceinline__ unsigned xb_add(unsigned* p, unsigned v) { return __hip_atomic_fetch_add(p, v, __ATOMIC_RELAXED, __HIP_MEMORY_SCOPE_AGENT); }
; __device__ __forceinline__ void xcd_barrier(const XcdBarrier& b) {
;     asm volatile("s_waitcnt vmcnt(0)" ::: "memory");
;     __syncthreads();
;     if (threadIdx.x == 0) {
;         unsigned* bar = b.bar;
;         __builtin_amdgcn_s_waitcnt(0);
;         unsigned nloc = b.st[0], nx = b.st[1];
;         if (nloc == 0u) { xcd_barrier_complete(bar, b.x, nloc, nx); b.st[0] = nloc; b.st[1] = nx; }
;         const unsigned old = xb_add(&bar[XB_XSUB(b.x)], 1u);
.LBB0_285:
	s_waitcnt vmcnt(0)
	s_barrier
	s_mov_b64 s[0:1], exec
	v_readlane_b32 s4, v254, 9
	v_readlane_b32 s5, v254, 10
	s_and_b64 s[4:5], s[0:1], s[4:5]
	s_mov_b64 exec, s[4:5]
	s_cbranch_execz .LBB0_335
	s_add_i32 s3, 0, 0x23fc0
	v_mov_b32_e32 v0, s3
	s_waitcnt vmcnt(0) expcnt(0) lgkmcnt(0)
	buffer_inv sc1
	ds_read_b32 v2, v0
	s_add_i32 s3, 0, 0x23fc4
	v_mov_b32_e32 v0, s3
	ds_read_b32 v0, v0
	s_waitcnt lgkmcnt(1)
	v_cmp_ne_u32_e32 vcc, 0, v2
	s_cbranch_vccnz .LBB0_301
	s_add_u32 s4, s30, 0x1000
	s_addc_u32 s5, s31, 0
	s_add_u32 s6, s30, 0x1100
	s_addc_u32 s7, s31, 0
	s_add_u32 s8, s30, 0x1200
	v_readlane_b32 s3, v254, 8
	s_addc_u32 s9, s31, 0
	s_mul_i32 s3, s87, s3
	s_add_u32 s20, s30, 0x1300
	s_mul_i32 s3, s3, s86
	s_addc_u32 s21, s31, 0
	s_mov_b32 s13, 1
	v_mov_b32_e32 v16, 0
	s_branch .LBB0_289

; __device__ __forceinline__ unsigned xb_add(unsigned* p, unsigned v) { return __hip_atomic_fetch_add(p, v, __ATOMIC_RELAXED, __HIP_MEMORY_SCOPE_AGENT); }
; __device__ __forceinline__ void xcd_barrier(const XcdBarrier& b) {
;     asm volatile("s_waitcnt vmcnt(0)" ::: "memory");
;     __syncthreads();
;     if (threadIdx.x == 0) {
;         unsigned* bar = b.bar;
;         __builtin_amdgcn_s_waitcnt(0);
;         unsigned nloc = b.st[0], nx = b.st[1];
;         if (nloc == 0u) { xcd_barrier_complete(bar, b.x, nloc, nx); b.st[0] = nloc; b.st[1] = nx; }
;         const unsigned old = xb_add(&bar[XB_XSUB(b.x)], 1u);
.LBB0_467:
	s_waitcnt vmcnt(0)
	s_barrier
	s_mov_b64 s[0:1], exec
	v_readlane_b32 s4, v254, 9
	v_readlane_b32 s5, v254, 10
	s_and_b64 s[4:5], s[0:1], s[4:5]
	s_mov_b64 exec, s[4:5]
	s_cbranch_execz .LBB0_517
	s_add_i32 s3, 0, 0x23fc0
	v_mov_b32_e32 v0, s3
	s_waitcnt vmcnt(0) expcnt(0) lgkmcnt(0)
	buffer_inv sc1
	ds_read_b32 v2, v0
	s_add_i32 s3, 0, 0x23fc4
	v_mov_b32_e32 v0, s3
	ds_read_b32 v0, v0
	s_waitcnt lgkmcnt(1)
	v_cmp_ne_u32_e32 vcc, 0, v2
	s_cbranch_vccnz .LBB0_483
	s_add_u32 s4, s30, 0x1000
	s_addc_u32 s5, s31, 0
	s_add_u32 s8, s30, 0x1100
	s_addc_u32 s9, s31, 0
	s_add_u32 s10, s30, 0x1200
	v_readlane_b32 s3, v254, 8
	s_addc_u32 s11, s31, 0
	s_mul_i32 s3, s87, s3
	s_add_u32 s18, s30, 0x1300
	s_mul_i32 s3, s3, s86
	s_addc_u32 s19, s31, 0
	s_mov_b32 s13, 1
	v_mov_b32_e32 v16, 0
	s_branch .LBB0_471

; __device__ __forceinline__ unsigned xb_add(unsigned* p, unsigned v) { return __hip_atomic_fetch_add(p, v, __ATOMIC_RELAXED, __HIP_MEMORY_SCOPE_AGENT); }
; __device__ __forceinline__ void xcd_barrier(const XcdBarrier& b) {
;     asm volatile("s_waitcnt vmcnt(0)" ::: "memory");
;     __syncthreads();
;     if (threadIdx.x == 0) {
;         unsigned* bar = b.bar;
;         __builtin_amdgcn_s_waitcnt(0);
;         unsigned nloc = b.st[0], nx = b.st[1];
;         if (nloc == 0u) { xcd_barrier_complete(bar, b.x, nloc, nx); b.st[0] = nloc; b.st[1] = nx; }
;         const unsigned old = xb_add(&bar[XB_XSUB(b.x)], 1u);
.LBB0_563:
	s_waitcnt vmcnt(0)
	s_barrier
	s_mov_b64 s[0:1], exec
	v_readlane_b32 s4, v254, 9
	v_readlane_b32 s5, v254, 10
	s_and_b64 s[4:5], s[0:1], s[4:5]
	s_mov_b64 exec, s[4:5]
	s_cbranch_execz .LBB0_613
	s_add_i32 s3, 0, 0x23fc0
	v_mov_b32_e32 v0, s3
	s_waitcnt vmcnt(0) expcnt(0) lgkmcnt(0)
	buffer_inv sc1
	ds_read_b32 v2, v0
	s_add_i32 s3, 0, 0x23fc4
	v_mov_b32_e32 v0, s3
	ds_read_b32 v0, v0
	s_waitcnt lgkmcnt(1)
	v_cmp_ne_u32_e32 vcc, 0, v2
	s_cbranch_vccnz .LBB0_579
	s_add_u32 s4, s30, 0x1000
	s_addc_u32 s5, s31, 0
	s_add_u32 s6, s30, 0x1100
	s_addc_u32 s7, s31, 0
	s_add_u32 s8, s30, 0x1200
	v_readlane_b32 s3, v254, 8
	s_addc_u32 s9, s31, 0
	s_mul_i32 s3, s87, s3
	s_add_u32 s10, s30, 0x1300
	s_mul_i32 s3, s3, s86
	s_addc_u32 s11, s31, 0
	s_mov_b32 s13, 1
	v_mov_b32_e32 v16, 0
	s_branch .LBB0_567

; __device__ __forceinline__ unsigned xb_add(unsigned* p, unsigned v) { return __hip_atomic_fetch_add(p, v, __ATOMIC_RELAXED, __HIP_MEMORY_SCOPE_AGENT); }
; __device__ __forceinline__ void xcd_barrier(const XcdBarrier& b) {
;     asm volatile("s_waitcnt vmcnt(0)" ::: "memory");
;     __syncthreads();
;     if (threadIdx.x == 0) {
;         unsigned* bar = b.bar;
;         __builtin_amdgcn_s_waitcnt(0);
;         unsigned nloc = b.st[0], nx = b.st[1];
;         if (nloc == 0u) { xcd_barrier_complete(bar, b.x, nloc, nx); b.st[0] = nloc; b.st[1] = nx; }
;         const unsigned old = xb_add(&bar[XB_XSUB(b.x)], 1u);
.LBB0_826:
	s_waitcnt vmcnt(0)
	s_barrier
	s_mov_b64 s[0:1], exec
	v_readlane_b32 s4, v254, 9
	v_readlane_b32 s5, v254, 10
	s_and_b64 s[4:5], s[0:1], s[4:5]
	s_mov_b64 exec, s[4:5]
	s_cbranch_execz .LBB0_876
	s_add_i32 s3, 0, 0x23fc0
	v_mov_b32_e32 v0, s3
	s_waitcnt vmcnt(0) expcnt(0) lgkmcnt(0)
	buffer_inv sc1
	ds_read_b32 v2, v0
	s_add_i32 s3, 0, 0x23fc4
	v_mov_b32_e32 v0, s3
	ds_read_b32 v0, v0
	s_waitcnt lgkmcnt(1)
	v_cmp_ne_u32_e32 vcc, 0, v2
	s_cbranch_vccnz .LBB0_842
	s_add_u32 s4, s30, 0x1000
	s_addc_u32 s5, s31, 0
	s_add_u32 s6, s30, 0x1100
	s_addc_u32 s7, s31, 0
	s_add_u32 s8, s30, 0x1200
	v_readlane_b32 s3, v254, 8
	s_addc_u32 s9, s31, 0
	s_mul_i32 s3, s87, s3
	s_add_u32 s10, s30, 0x1300
	s_mul_i32 s3, s3, s86
	s_addc_u32 s11, s31, 0
	s_mov_b32 s18, 1
	v_mov_b32_e32 v16, 0
	s_branch .LBB0_830

; __device__ __forceinline__ unsigned xb_add(unsigned* p, unsigned v) { return __hip_atomic_fetch_add(p, v, __ATOMIC_RELAXED, __HIP_MEMORY_SCOPE_AGENT); }
; __device__ __forceinline__ void xcd_barrier(const XcdBarrier& b) {
;     asm volatile("s_waitcnt vmcnt(0)" ::: "memory");
;     __syncthreads();
;     if (threadIdx.x == 0) {
;         unsigned* bar = b.bar;
;         __builtin_amdgcn_s_waitcnt(0);
;         unsigned nloc = b.st[0], nx = b.st[1];
;         if (nloc == 0u) { xcd_barrier_complete(bar, b.x, nloc, nx); b.st[0] = nloc; b.st[1] = nx; }
;         const unsigned old = xb_add(&bar[XB_XSUB(b.x)], 1u);
.LBB0_1027:
	s_waitcnt vmcnt(0)
	s_barrier
	s_mov_b64 s[0:1], exec
	v_readlane_b32 s4, v254, 9
	v_readlane_b32 s5, v254, 10
	s_and_b64 s[4:5], s[0:1], s[4:5]
	s_mov_b64 exec, s[4:5]
	s_cbranch_execz .LBB0_1077
	s_add_i32 s3, 0, 0x23fc0
	v_mov_b32_e32 v0, s3
	s_waitcnt vmcnt(0) expcnt(0) lgkmcnt(0)
	buffer_inv sc1
	ds_read_b32 v2, v0
	s_add_i32 s3, 0, 0x23fc4
	v_mov_b32_e32 v0, s3
	ds_read_b32 v0, v0
	s_waitcnt lgkmcnt(1)
	v_cmp_ne_u32_e32 vcc, 0, v2
	s_cbranch_vccnz .LBB0_1043
	s_add_u32 s4, s30, 0x1000
	s_addc_u32 s5, s31, 0
	s_add_u32 s8, s30, 0x1100
	s_addc_u32 s9, s31, 0
	s_add_u32 s10, s30, 0x1200
	v_readlane_b32 s3, v254, 8
	s_addc_u32 s11, s31, 0
	s_mul_i32 s3, s87, s3
	s_add_u32 s12, s30, 0x1300
	s_mul_i32 s3, s3, s86
	s_addc_u32 s13, s31, 0
	s_mov_b32 s20, 1
	v_mov_b32_e32 v16, 0
	s_branch .LBB0_1031
